# FFN-up k-loop: loads take a 32-bit per-lane offset plus the running scalar base (saddr form) instead of a 64-bit VALU address add per load
# speedup vs baseline: 1.0289x; 1.0020x over previous
.LBB0_669:
	s_or_b64 exec, exec, s[18:19]
	v_add_co_u32_e32 v4, vcc, 0x7000, v30
	s_mul_i32 s18, s52, 62
	s_nop 0
	v_addc_co_u32_e32 v5, vcc, 0, v31, vcc
	global_load_dwordx4 v[110:113], v[4:5], off
	v_ashrrev_i32_e32 v4, 3, v41
	s_add_i32 s18, s3, s18
	v_lshrrev_b32_e32 v116, 4, v4
	s_add_i32 s18, s18, s51
	v_ashrrev_i32_e32 v8, 3, v40
	v_lshlrev_b64 v[4:5], 18, v[116:117]
	s_lshl_b32 s18, s18, 1
	v_lshl_add_u64 v[2:3], v[2:3], 1, v[4:5]
	v_lshrrev_b32_e32 v116, 4, v8
	v_subrev_u16_e32 v4, s18, v163
	v_ashrrev_i32_e32 v7, 3, v39
	v_lshl_add_u64 v[128:129], v[122:123], 0, v[2:3]
	v_lshlrev_b64 v[2:3], 18, v[116:117]
	v_and_b32_e32 v4, 0x7f, v4
	s_waitcnt lgkmcnt(0)
	s_barrier
	ds_read_b128 v[102:105], v168 offset:18432
	ds_read_b128 v[94:97], v168 offset:23040
	ds_read_b128 v[106:109], v169
	ds_read_b128 v[98:101], v169 offset:4608
	v_lshl_or_b32 v2, v4, 7, v2
	v_lshrrev_b32_e32 v116, 4, v7
	v_subrev_u16_e32 v4, s18, v164
	v_ashrrev_i32_e32 v6, 3, v38
	v_lshl_add_u64 v[130:131], v[122:123], 0, v[2:3]
	v_lshlrev_b64 v[2:3], 18, v[116:117]
	v_and_b32_e32 v4, 0x7f, v4
	v_lshl_or_b32 v2, v4, 7, v2
	v_lshrrev_b32_e32 v116, 4, v6
	v_subrev_u16_e32 v4, s18, v165
	v_lshl_add_u64 v[132:133], v[122:123], 0, v[2:3]
	v_lshlrev_b64 v[2:3], 18, v[116:117]
	v_and_b32_e32 v4, 0x7f, v4
	v_lshl_or_b32 v2, v4, 7, v2
	v_lshl_add_u64 v[134:135], v[122:123], 0, v[2:3]
	v_mov_b32_e32 v2, 0
	s_mov_b32 s15, 0
	v_lshl_add_u64 v[136:137], v[124:125], 0, s[16:17]
	s_mov_b64 s[16:17], 0
	v_mov_b32_e32 v3, v2
	v_mov_b32_e32 v4, v2
	v_mov_b32_e32 v5, v2
	v_mov_b32_e32 v6, v2
	v_mov_b32_e32 v7, v2
	v_mov_b32_e32 v8, v2
	v_mov_b32_e32 v9, v2
	v_mov_b32_e32 v10, v2
	v_mov_b32_e32 v11, v2
	v_mov_b32_e32 v12, v2
	v_mov_b32_e32 v13, v2
	v_mov_b32_e32 v14, v2
	v_mov_b32_e32 v15, v2
	v_mov_b32_e32 v16, v2
	v_mov_b32_e32 v17, v2
	v_mov_b32_e32 v18, v2
	v_mov_b32_e32 v19, v2
	v_mov_b32_e32 v20, v2
	v_mov_b32_e32 v21, v2
	v_mov_b32_e32 v22, v2
	v_mov_b32_e32 v23, v2
	v_mov_b32_e32 v24, v2
	v_mov_b32_e32 v25, v2
	v_mov_b32_e32 v26, v2
	v_mov_b32_e32 v27, v2
	v_mov_b32_e32 v28, v2
	v_mov_b32_e32 v29, v2
	v_mov_b32_e32 v30, v2
	v_mov_b32_e32 v31, v2
	v_mov_b32_e32 v32, v2
	v_mov_b32_e32 v33, v2
	v_mov_b32_e32 v34, v2
	v_mov_b32_e32 v35, v2
	v_mov_b32_e32 v36, v2
	v_mov_b32_e32 v37, v2
	v_mov_b32_e32 v38, v2
	v_mov_b32_e32 v39, v2
	v_mov_b32_e32 v40, v2
	v_mov_b32_e32 v41, v2
	v_mov_b32_e32 v42, v2
	v_mov_b32_e32 v43, v2
	v_mov_b32_e32 v44, v2
	v_mov_b32_e32 v45, v2
	v_mov_b32_e32 v46, v2
	v_mov_b32_e32 v47, v2
	v_mov_b32_e32 v48, v2
	v_mov_b32_e32 v49, v2
	v_mov_b32_e32 v50, v2
	v_mov_b32_e32 v51, v2
	v_mov_b32_e32 v52, v2
	v_mov_b32_e32 v53, v2
	v_mov_b32_e32 v54, v2
	v_mov_b32_e32 v55, v2
	v_mov_b32_e32 v56, v2
	v_mov_b32_e32 v57, v2
	v_mov_b32_e32 v58, v2
	v_mov_b32_e32 v59, v2
	v_mov_b32_e32 v60, v2
	v_mov_b32_e32 v61, v2
	v_mov_b32_e32 v62, v2
	v_mov_b32_e32 v63, v2
	v_mov_b32_e32 v64, v2
	v_mov_b32_e32 v65, v2
	s_sub_u32 s62, 0x102c000, s34
	v_add_u32_e32 v220, s62, v136
	s_sub_u32 s62, 0x102d000, s34
	v_add_u32_e32 v221, s62, v136
	s_sub_u32 s62, 0x102e000, s34
	v_add_u32_e32 v222, s62, v136
	s_sub_u32 s62, 0x102f000, s34
	v_add_u32_e32 v223, s62, v136
	v_subrev_u32_e32 v224, s34, v134
	v_subrev_u32_e32 v225, s34, v132
	v_subrev_u32_e32 v226, s34, v130
	v_subrev_u32_e32 v227, s34, v128
	s_mov_b32 s64, s34
	s_mov_b32 s65, s35
	s_mov_b32 s66, 7
.Lk5_loop:
	ds_read_b128 v[172:175], v168 offset:18464
	ds_read_b128 v[176:179], v168 offset:23072
	ds_read_b128 v[180:183], v169 offset:32
	ds_read_b128 v[184:187], v169 offset:4640
	s_waitcnt lgkmcnt(4)
	v_mfma_f32_32x32x16_bf16 v[50:65], v[102:105], v[106:109], v[50:65]
	s_waitcnt vmcnt(7)
	ds_write_b128 v140, v[66:69] offset:36864
	v_mfma_f32_32x32x16_bf16 v[34:49], v[94:97], v[106:109], v[34:49]
	s_waitcnt vmcnt(6)
	ds_write_b128 v140, v[74:77] offset:55296
	v_mfma_f32_32x32x16_bf16 v[18:33], v[102:105], v[98:101], v[18:33]
	s_waitcnt vmcnt(5)
	ds_write_b128 v142, v[70:73] offset:36864
	v_mfma_f32_32x32x16_bf16 v[2:17], v[94:97], v[98:101], v[2:17]
	s_waitcnt vmcnt(4)
	ds_write_b128 v142, v[82:85] offset:55296
	ds_read_b128 v[102:105], v168 offset:18496
	ds_read_b128 v[94:97], v168 offset:23104
	ds_read_b128 v[106:109], v169 offset:64
	ds_read_b128 v[98:101], v169 offset:4672
	s_waitcnt lgkmcnt(4)
	v_mfma_f32_32x32x16_bf16 v[50:65], v[172:175], v[180:183], v[50:65]
	s_waitcnt vmcnt(3)
	ds_write_b128 v144, v[78:81] offset:36864
	v_mfma_f32_32x32x16_bf16 v[34:49], v[176:179], v[180:183], v[34:49]
	s_waitcnt vmcnt(2)
	ds_write_b128 v144, v[86:89] offset:55296
	v_mfma_f32_32x32x16_bf16 v[18:33], v[172:175], v[184:187], v[18:33]
	s_waitcnt vmcnt(1)
	ds_write_b128 v146, v[90:93] offset:36864
	v_mfma_f32_32x32x16_bf16 v[2:17], v[176:179], v[184:187], v[2:17]
	s_waitcnt vmcnt(0)
	ds_write_b128 v146, v[110:113] offset:55296
	ds_read_b128 v[172:175], v168 offset:18528
	ds_read_b128 v[176:179], v168 offset:23136
	ds_read_b128 v[180:183], v169 offset:96
	ds_read_b128 v[184:187], v169 offset:4704
	s_waitcnt lgkmcnt(8)
	v_mfma_f32_32x32x16_bf16 v[50:65], v[102:105], v[106:109], v[50:65]
	s_mov_b64 exec, s[4:5]
	global_load_dwordx4 v[66:69], v224, s[64:65]
	s_mov_b64 exec, -1
	global_load_dwordx4 v[74:77], v220, s[64:65]
	v_mfma_f32_32x32x16_bf16 v[34:49], v[94:97], v[106:109], v[34:49]
	s_mov_b64 exec, s[6:7]
	global_load_dwordx4 v[70:73], v225, s[64:65]
	s_mov_b64 exec, -1
	global_load_dwordx4 v[82:85], v221, s[64:65]
	v_mfma_f32_32x32x16_bf16 v[18:33], v[102:105], v[98:101], v[18:33]
	s_mov_b64 exec, s[8:9]
	global_load_dwordx4 v[78:81], v226, s[64:65]
	s_mov_b64 exec, -1
	global_load_dwordx4 v[86:89], v222, s[64:65]
	v_mfma_f32_32x32x16_bf16 v[2:17], v[94:97], v[98:101], v[2:17]
	s_mov_b64 exec, s[10:11]
	global_load_dwordx4 v[90:93], v227, s[64:65]
	s_mov_b64 exec, -1
	global_load_dwordx4 v[110:113], v223, s[64:65]
	s_add_u32 s64, s64, 0x4000
	s_addc_u32 s65, s65, 0
	s_waitcnt lgkmcnt(0)
	s_barrier
	ds_read_b128 v[102:105], v168 offset:55296
	ds_read_b128 v[94:97], v168 offset:59904
	ds_read_b128 v[106:109], v169 offset:36864
	ds_read_b128 v[98:101], v169 offset:41472
	v_mfma_f32_32x32x16_bf16 v[50:65], v[172:175], v[180:183], v[50:65]
	v_mfma_f32_32x32x16_bf16 v[34:49], v[176:179], v[180:183], v[34:49]
	v_mfma_f32_32x32x16_bf16 v[18:33], v[172:175], v[184:187], v[18:33]
	v_mfma_f32_32x32x16_bf16 v[2:17], v[176:179], v[184:187], v[2:17]
	ds_read_b128 v[172:175], v168 offset:55328
	ds_read_b128 v[176:179], v168 offset:59936
	ds_read_b128 v[180:183], v169 offset:36896
	ds_read_b128 v[184:187], v169 offset:41504
	s_waitcnt lgkmcnt(4)
	v_mfma_f32_32x32x16_bf16 v[50:65], v[102:105], v[106:109], v[50:65]
	s_waitcnt vmcnt(7)
	ds_write_b128 v140, v[66:69]
	v_mfma_f32_32x32x16_bf16 v[34:49], v[94:97], v[106:109], v[34:49]
	s_waitcnt vmcnt(6)
	ds_write_b128 v140, v[74:77] offset:18432
	v_mfma_f32_32x32x16_bf16 v[18:33], v[102:105], v[98:101], v[18:33]
	s_waitcnt vmcnt(5)
	ds_write_b128 v142, v[70:73]
	v_mfma_f32_32x32x16_bf16 v[2:17], v[94:97], v[98:101], v[2:17]
	s_waitcnt vmcnt(4)
	ds_write_b128 v142, v[82:85] offset:18432
	ds_read_b128 v[102:105], v168 offset:55360
	ds_read_b128 v[94:97], v168 offset:59968
	ds_read_b128 v[106:109], v169 offset:36928
	ds_read_b128 v[98:101], v169 offset:41536
	s_waitcnt lgkmcnt(4)
	v_mfma_f32_32x32x16_bf16 v[50:65], v[172:175], v[180:183], v[50:65]
	s_waitcnt vmcnt(3)
	ds_write_b128 v144, v[78:81]
	v_mfma_f32_32x32x16_bf16 v[34:49], v[176:179], v[180:183], v[34:49]
	s_waitcnt vmcnt(2)
	ds_write_b128 v144, v[86:89] offset:18432
	v_mfma_f32_32x32x16_bf16 v[18:33], v[172:175], v[184:187], v[18:33]
	s_waitcnt vmcnt(1)
	ds_write_b128 v146, v[90:93]
	v_mfma_f32_32x32x16_bf16 v[2:17], v[176:179], v[184:187], v[2:17]
	s_waitcnt vmcnt(0)
	ds_write_b128 v146, v[110:113] offset:18432
	ds_read_b128 v[172:175], v168 offset:55392
	ds_read_b128 v[176:179], v168 offset:60000
	ds_read_b128 v[180:183], v169 offset:36960
	ds_read_b128 v[184:187], v169 offset:41568
	s_waitcnt lgkmcnt(8)
	v_mfma_f32_32x32x16_bf16 v[50:65], v[102:105], v[106:109], v[50:65]
	s_mov_b64 exec, s[4:5]
	global_load_dwordx4 v[66:69], v224, s[64:65]
	s_mov_b64 exec, -1
	global_load_dwordx4 v[74:77], v220, s[64:65]
	v_mfma_f32_32x32x16_bf16 v[34:49], v[94:97], v[106:109], v[34:49]
	s_mov_b64 exec, s[6:7]
	global_load_dwordx4 v[70:73], v225, s[64:65]
	s_mov_b64 exec, -1
	global_load_dwordx4 v[82:85], v221, s[64:65]
	v_mfma_f32_32x32x16_bf16 v[18:33], v[102:105], v[98:101], v[18:33]
	s_mov_b64 exec, s[8:9]
	global_load_dwordx4 v[78:81], v226, s[64:65]
	s_mov_b64 exec, -1
	global_load_dwordx4 v[86:89], v222, s[64:65]
	v_mfma_f32_32x32x16_bf16 v[2:17], v[94:97], v[98:101], v[2:17]
	s_mov_b64 exec, s[10:11]
	global_load_dwordx4 v[90:93], v227, s[64:65]
	s_mov_b64 exec, -1
	global_load_dwordx4 v[110:113], v223, s[64:65]
	s_add_u32 s64, s64, 0x4000
	s_addc_u32 s65, s65, 0
	s_waitcnt lgkmcnt(0)
	s_barrier
	ds_read_b128 v[102:105], v168 offset:18432
	ds_read_b128 v[94:97], v168 offset:23040
	ds_read_b128 v[106:109], v169
	ds_read_b128 v[98:101], v169 offset:4608
	v_mfma_f32_32x32x16_bf16 v[50:65], v[172:175], v[180:183], v[50:65]
	v_mfma_f32_32x32x16_bf16 v[34:49], v[176:179], v[180:183], v[34:49]
	v_mfma_f32_32x32x16_bf16 v[18:33], v[172:175], v[184:187], v[18:33]
	v_mfma_f32_32x32x16_bf16 v[2:17], v[176:179], v[184:187], v[2:17]
	s_sub_u32 s66, s66, 1
	s_cmp_lg_u32 s66, 0
	s_cbranch_scc1 .Lk5_loop
	s_branch .LBB0_679

.LBB0_2386:
	s_or_b64 exec, exec, s[22:23]
	v_add_co_u32_e32 v4, vcc, 0x7000, v30
	s_mul_i32 s22, s38, 62
	s_nop 0
	v_addc_co_u32_e32 v5, vcc, 0, v31, vcc
	global_load_dwordx4 v[110:113], v[4:5], off
	v_ashrrev_i32_e32 v4, 3, v41
	s_add_i32 s22, s24, s22
	v_lshrrev_b32_e32 v116, 4, v4
	s_add_i32 s22, s22, s37
	v_ashrrev_i32_e32 v8, 3, v40
	v_lshlrev_b64 v[4:5], 18, v[116:117]
	s_lshl_b32 s22, s22, 1
	v_lshl_add_u64 v[2:3], v[2:3], 1, v[4:5]
	v_lshrrev_b32_e32 v116, 4, v8
	v_subrev_u16_e32 v4, s22, v163
	v_ashrrev_i32_e32 v7, 3, v39
	v_lshl_add_u64 v[128:129], v[122:123], 0, v[2:3]
	v_lshlrev_b64 v[2:3], 18, v[116:117]
	v_and_b32_e32 v4, 0x7f, v4
	s_waitcnt lgkmcnt(0)
	s_barrier
	ds_read_b128 v[102:105], v168 offset:18432
	ds_read_b128 v[94:97], v168 offset:23040
	ds_read_b128 v[106:109], v169
	ds_read_b128 v[98:101], v169 offset:4608
	v_lshl_or_b32 v2, v4, 7, v2
	v_lshrrev_b32_e32 v116, 4, v7
	v_subrev_u16_e32 v4, s22, v164
	v_ashrrev_i32_e32 v6, 3, v38
	v_lshl_add_u64 v[130:131], v[122:123], 0, v[2:3]
	v_lshlrev_b64 v[2:3], 18, v[116:117]
	v_and_b32_e32 v4, 0x7f, v4
	v_lshl_or_b32 v2, v4, 7, v2
	v_lshrrev_b32_e32 v116, 4, v6
	v_subrev_u16_e32 v4, s22, v165
	v_lshl_add_u64 v[132:133], v[122:123], 0, v[2:3]
	v_lshlrev_b64 v[2:3], 18, v[116:117]
	v_and_b32_e32 v4, 0x7f, v4
	v_lshl_or_b32 v2, v4, 7, v2
	v_lshl_add_u64 v[134:135], v[122:123], 0, v[2:3]
	v_mov_b32_e32 v2, 0
	s_mov_b32 s19, 0
	v_lshl_add_u64 v[136:137], v[124:125], 0, s[20:21]
	s_mov_b64 s[20:21], 0
	v_mov_b32_e32 v3, v2
	v_mov_b32_e32 v4, v2
	v_mov_b32_e32 v5, v2
	v_mov_b32_e32 v6, v2
	v_mov_b32_e32 v7, v2
	v_mov_b32_e32 v8, v2
	v_mov_b32_e32 v9, v2
	v_mov_b32_e32 v10, v2
	v_mov_b32_e32 v11, v2
	v_mov_b32_e32 v12, v2
	v_mov_b32_e32 v13, v2
	v_mov_b32_e32 v14, v2
	v_mov_b32_e32 v15, v2
	v_mov_b32_e32 v16, v2
	v_mov_b32_e32 v17, v2
	v_mov_b32_e32 v18, v2
	v_mov_b32_e32 v19, v2
	v_mov_b32_e32 v20, v2
	v_mov_b32_e32 v21, v2
	v_mov_b32_e32 v22, v2
	v_mov_b32_e32 v23, v2
	v_mov_b32_e32 v24, v2
	v_mov_b32_e32 v25, v2
	v_mov_b32_e32 v26, v2
	v_mov_b32_e32 v27, v2
	v_mov_b32_e32 v28, v2
	v_mov_b32_e32 v29, v2
	v_mov_b32_e32 v30, v2
	v_mov_b32_e32 v31, v2
	v_mov_b32_e32 v32, v2
	v_mov_b32_e32 v33, v2
	v_mov_b32_e32 v34, v2
	v_mov_b32_e32 v35, v2
	v_mov_b32_e32 v36, v2
	v_mov_b32_e32 v37, v2
	v_mov_b32_e32 v38, v2
	v_mov_b32_e32 v39, v2
	v_mov_b32_e32 v40, v2
	v_mov_b32_e32 v41, v2
	v_mov_b32_e32 v42, v2
	v_mov_b32_e32 v43, v2
	v_mov_b32_e32 v44, v2
	v_mov_b32_e32 v45, v2
	v_mov_b32_e32 v46, v2
	v_mov_b32_e32 v47, v2
	v_mov_b32_e32 v48, v2
	v_mov_b32_e32 v49, v2
	v_mov_b32_e32 v50, v2
	v_mov_b32_e32 v51, v2
	v_mov_b32_e32 v52, v2
	v_mov_b32_e32 v53, v2
	v_mov_b32_e32 v54, v2
	v_mov_b32_e32 v55, v2
	v_mov_b32_e32 v56, v2
	v_mov_b32_e32 v57, v2
	v_mov_b32_e32 v58, v2
	v_mov_b32_e32 v59, v2
	v_mov_b32_e32 v60, v2
	v_mov_b32_e32 v61, v2
	v_mov_b32_e32 v62, v2
	v_mov_b32_e32 v63, v2
	v_mov_b32_e32 v64, v2
	v_mov_b32_e32 v65, v2
	s_sub_u32 s62, 0x1b2c000, s34
	v_add_u32_e32 v220, s62, v136
	s_sub_u32 s62, 0x1b2d000, s34
	v_add_u32_e32 v221, s62, v136
	s_sub_u32 s62, 0x1b2e000, s34
	v_add_u32_e32 v222, s62, v136
	s_sub_u32 s62, 0x1b2f000, s34
	v_add_u32_e32 v223, s62, v136
	v_subrev_u32_e32 v224, s34, v134
	v_subrev_u32_e32 v225, s34, v132
	v_subrev_u32_e32 v226, s34, v130
	v_subrev_u32_e32 v227, s34, v128
	s_mov_b32 s64, s34
	s_mov_b32 s65, s35
	s_mov_b32 s66, 7
